# v15 + grid barriers after the sample-row reduces of phases 3 and 11 replaced by completion counters (only workgroups that own sample-row GEMM tiles wait)
# speedup vs baseline: 1.0140x; 1.0057x over previous
; #define CASE(k) if (PH_ON(k) && ph_lo <= (k) && (k) < ph_hi)
; #define SEAM(k) if (ph_lo <= (k) && (k) < ph_hi && ph_hi - ph_lo > 1) xcd_barrier(bar);
; __device__ __forceinline__ void xcd_barrier(const XcdBarrier& b) {
;     asm volatile("s_waitcnt vmcnt(0)" ::: "memory");
;     __syncthreads();
;     if (threadIdx.x == 0) {
; __global__ void __launch_bounds__(512, 2) mega(Params p) {
;     ...
;         CASE(3) sample_reduce<0>((const float*)(ws + O_SLAB), 11, nullptr, nullptr, 0.5f, nullptr, nullptr, nullptr, XB, (float*)(ws + O_ST1), nullptr, nullptr, XB); SEAM(3)
.LBB0_359:
	s_or_b64 exec, exec, s[6:7]
	s_waitcnt vmcnt(0) lgkmcnt(0)
	s_barrier
	s_cmpk_gt_u32 s2, 0x7f
	s_cbranch_scc1 .Lq3_prod_done
	s_mov_b64 s[38:39], exec
	v_readlane_b32 s0, v252, 6
	v_readlane_b32 s1, v252, 7
	s_and_b64 s[0:1], s[38:39], s[0:1]
	s_mov_b64 exec, s[0:1]
	s_cbranch_execz .Lq3_prod_restore
	buffer_wbl2 sc1
	s_waitcnt vmcnt(0)
	s_add_u32 s98, s52, 0x2fb46880
	s_addc_u32 s99, s53, 0
	v_mov_b32_e32 v0, 0
	v_mov_b32_e32 v1, 1
	global_atomic_add v0, v1, s[98:99]
	s_waitcnt vmcnt(0)

; __device__ __forceinline__ unsigned xb_ld(unsigned* p)              { return __hip_atomic_load(p, __ATOMIC_RELAXED, __HIP_MEMORY_SCOPE_AGENT); }
; __device__ __forceinline__ void xcd_barrier_complete(unsigned* bar, unsigned x, unsigned& nloc, unsigned& nx) {
;     const unsigned G = gridDim.x * gridDim.y * gridDim.z;
;     unsigned sum, cnt, mine, sp = 0u;
;     for (;;) {
;         sum = 0u; cnt = 0u; mine = 0u;
; #pragma unroll
;         for (unsigned j = 0; j < 16; ++j) { const unsigned c = xb_ld(&bar[XB_XCNT(j)]); sum += c; cnt += (c > 0u) ? 1u : 0u; mine = (j == x) ? c : mine; }
;         if (sum == G) break;
;         __builtin_amdgcn_s_sleep(1);
;         if ((++sp & 255u) == 0u) { if (xb_ld(&bar[XB_TMO])) break; if (sp > XB_SPIN_CAP) { atomicAdd(&bar[XB_TMO], 1u); break; } }
;     }
;     nloc = mine > 0u ? mine : 1u; nx = cnt > 0u ? cnt : 1u;
; }
; __device__ __forceinline__ void xcd_barrier(const XcdBarrier& b) {
;     asm volatile("s_waitcnt vmcnt(0)" ::: "memory");
;     __syncthreads();
;     if (threadIdx.x == 0) {
;         unsigned* bar = b.bar;
;         __builtin_amdgcn_s_waitcnt(0);
;         unsigned nloc = b.st[0], nx = b.st[1];
;         if (nloc == 0u) { xcd_barrier_complete(bar, b.x, nloc, nx); b.st[0] = nloc; b.st[1] = nx; }
.Lq3_prod_done:
	s_branch .LBB0_405
	v_readlane_b32 s0, v252, 12
	v_readlane_b32 s1, v252, 13
	s_andn2_b64 vcc, exec, s[0:1]
	s_cbranch_vccnz .LBB0_405
	s_waitcnt vmcnt(0)
	s_waitcnt vmcnt(0) lgkmcnt(0)
	s_barrier
	s_mov_b64 s[38:39], exec
	v_readlane_b32 s0, v252, 6
	v_readlane_b32 s1, v252, 7
	s_and_b64 s[0:1], s[38:39], s[0:1]
	s_mov_b64 exec, s[0:1]
	s_cbranch_execz .LBB0_404
	s_add_i32 s0, 0, 0x23f10
	v_mov_b32_e32 v0, s0
	s_waitcnt vmcnt(0) expcnt(0) lgkmcnt(0)
	ds_read_b32 v2, v0
	s_add_i32 s0, 0, 0x23f14
	v_mov_b32_e32 v0, s0
	ds_read_b32 v0, v0
	s_waitcnt lgkmcnt(1)
	v_cmp_ne_u32_e32 vcc, 0, v2
	s_cbranch_vccnz .LBB0_375
	s_add_u32 s6, s52, 0x2fb43200
	s_addc_u32 s7, s53, 0
	s_add_u32 s4, s52, 0x2fb43400
	s_addc_u32 s5, s53, 0
	s_add_u32 s10, s52, 0x2fb43500
	s_addc_u32 s11, s53, 0
	s_add_u32 s12, s52, 0x2fb43600
	s_addc_u32 s13, s53, 0
	s_add_u32 s14, s52, 0x2fb43700
	s_addc_u32 s15, s53, 0
	s_add_u32 s16, s52, 0x2fb43800
	s_addc_u32 s17, s53, 0
	s_add_u32 s18, s52, 0x2fb43900
	s_addc_u32 s19, s53, 0
	s_add_u32 s20, s52, 0x2fb43a00
	s_addc_u32 s21, s53, 0
	s_add_u32 s22, s52, 0x2fb43b00
	s_addc_u32 s23, s53, 0
	s_add_u32 s24, s52, 0x2fb43c00
	s_addc_u32 s25, s53, 0
	s_add_u32 s26, s52, 0x2fb43d00
	s_addc_u32 s27, s53, 0
	s_add_u32 s28, s52, 0x2fb43e00
	s_addc_u32 s29, s53, 0
	s_add_u32 s30, s52, 0x2fb43f00
	s_addc_u32 s31, s53, 0
	s_add_u32 s34, s52, 0x2fb44000
	s_addc_u32 s35, s53, 0
	s_add_u32 s36, s52, 0x2fb44100
	s_addc_u32 s37, s53, 0
	s_add_u32 s40, s52, 0x2fb44200
	s_addc_u32 s41, s53, 0
	v_readlane_b32 s0, v252, 0
	s_add_u32 s46, s52, 0x2fb44300
	s_mul_i32 s0, s83, s0
	s_addc_u32 s47, s53, 0
	s_mul_i32 s0, s0, s82
	s_mov_b32 s1, 1
	s_mov_b64 s[8:9], 0
	s_waitcnt lgkmcnt(0)
	v_mov_b64_e32 v[0:1], s[4:5]
	v_mov_b64_e32 v[2:3], s[10:11]
	v_mov_b64_e32 v[4:5], s[12:13]
	v_mov_b64_e32 v[6:7], s[14:15]
	v_mov_b64_e32 v[8:9], s[16:17]
	v_mov_b64_e32 v[10:11], s[18:19]
	v_mov_b64_e32 v[12:13], s[20:21]
	v_mov_b64_e32 v[14:15], s[22:23]
	v_mov_b64_e32 v[16:17], s[24:25]
	v_mov_b64_e32 v[18:19], s[26:27]
	v_mov_b64_e32 v[20:21], s[28:29]
	v_mov_b64_e32 v[22:23], s[30:31]
	v_mov_b64_e32 v[24:25], s[34:35]
	v_mov_b64_e32 v[26:27], s[36:37]
	v_mov_b64_e32 v[28:29], s[40:41]
	v_mov_b64_e32 v[30:31], s[46:47]
	s_branch .LBB0_365

; #define CASE(k) if (PH_ON(k) && ph_lo <= (k) && (k) < ph_hi)
; #define SEAM(k) if (ph_lo <= (k) && (k) < ph_hi && ph_hi - ph_lo > 1) xcd_barrier(bar);
; __global__ void __launch_bounds__(512, 2) mega(Params p) {
;     ...
;         CASE(4) { pg8::Gemm g{XB, (const bf16_t*)(ws + O_WIN), M, INC, D, D}; pg8::StaticOrder S; S.init(M, INC, G, bx);
;             pg8::EpiIn E{(bf16_t*)(ws + O_QB), (bf16_t*)(ws + O_KB), (bf16_t*)(ws + O_VB), (bf16_t*)(ws + O_UB), (float*)(ws + O_GVF), p.out, 0.125f * LOG2E, (const float*)(ws + O_ST1), (const float*)(ws + O_C1) + C_IN, (const float*)(ws + O_C2) + C_IN, (float*)(ws + O_GST)};
;             pg8::gemm_phase<pg8::EpiIn, pg8::StaticOrder, true, true>(lds, g, S, E); } SEAM(4)
.LBB0_405:
	s_cmp_lt_i32 s54, 5
	s_cselect_b64 s[0:1], -1, 0
	s_cmp_gt_i32 s55, 4
	s_cselect_b64 s[4:5], -1, 0
	s_and_b64 s[0:1], s[0:1], s[4:5]
	s_andn2_b64 vcc, exec, s[0:1]
	s_cbranch_vccnz .LBB0_866
	s_and_b32 s98, s2, 7
	s_cmp_lg_u32 s98, 7
	s_cbranch_scc1 .Lq3_skip
	s_add_u32 s98, s52, 0x2fb46880
	s_addc_u32 s99, s53, 0
	s_mov_b32 s101, 0
	v_mov_b32_e32 v0, 0

;     __host__ __device__ bool next(int i, Unit& u) const {
;         const long L = (long)i * G + c; if (L >= nwg) return false;
;         int wgid = (int)L; { const int q = nwg / NXCD, r = nwg % NXCD, xcd = wgid % NXCD, off = wgid / NXCD; wgid = (xcd < r ? xcd * (q + 1) : r * (q + 1) + (xcd - r) * q) + off; }
;         const int nig = WGM * nN, gid = wgid / nig, fm = gid * WGM, gsz = (nM - fm) < WGM ? (nM - fm) : WGM;
;         u.pm = fm + ((wgid % nig) % gsz); u.pn = (wgid % nig) / gsz; u.kofs = 0; return true;
;     }
; template <class Epi, class Sched, bool ALIGN_EPI = false, bool SP2 = false>
; __device__ __forceinline__ void gemm_phase(LAS unsigned char* lds, const Gemm g, const Sched& S, const Epi& E) {
;     ...
;     Unit cur, nxt; int ui = 0;
;     if (!S.next(0, cur)) return;
.Lq3_skip:
	v_mov_b32_e32 v8, v208
	s_cmpk_lt_i32 s2, 0x528
	s_cselect_b64 s[6:7], -1, 0
	s_cmpk_gt_i32 s2, 0x527
	v_readfirstlane_b32 s4, v8
	s_cbranch_scc1 .LBB0_408
	s_lshr_b32 s0, s3, 29
	s_add_i32 s0, s2, s0
	s_ashr_i32 s1, s0, 3
	s_and_b32 s0, s0, -8
	s_sub_i32 s0, s2, s0
	s_cmp_lt_i32 s0, 0
	s_movk_i32 s5, 0xa6
	s_cselect_b32 s5, s5, 0xa5
	s_mul_i32 s0, s0, s5
	s_add_i32 s0, s0, s1
	s_mul_hi_i32 s1, s0, 0x66666667
	s_lshr_b32 s5, s1, 31
	s_ashr_i32 s1, s1, 5
	s_add_i32 s1, s1, s5
	s_lshl_b32 s5, s1, 3
	s_sub_i32 s8, 0x84, s5
	s_mulk_i32 s1, 0x50
	s_min_u32 s8, s8, 8
	s_sub_i32 s9, s0, s1
	s_sext_i32_i8 s0, s9
	v_cvt_f32_ubyte0_e32 v1, s8
	v_cvt_f32_i32_e32 v0, s0
	s_waitcnt lgkmcnt(0)
	v_rcp_iflag_f32_e32 v2, v1
	s_ashr_i32 s0, s0, 30
	s_or_b32 s10, s0, 1
	v_mul_f32_e32 v2, v0, v2
	v_trunc_f32_e32 v2, v2
	v_fma_f32 v0, -v2, v1, v0
	v_cvt_i32_f32_e32 v2, v2
	v_cmp_ge_f32_e64 s[0:1], |v0|, v1
	s_and_b64 s[0:1], s[0:1], exec
	s_cselect_b32 s0, s10, 0
	v_readfirstlane_b32 s1, v2
	s_add_i32 s0, s1, s0
	s_sext_i32_i8 s24, s0
	s_mul_i32 s0, s0, s8
	s_sub_i32 s0, s9, s0
	s_sext_i32_i8 s0, s0
	s_add_i32 s12, s5, s0

; #define CASE(k) if (PH_ON(k) && ph_lo <= (k) && (k) < ph_hi)
; #define SEAM(k) if (ph_lo <= (k) && (k) < ph_hi && ph_hi - ph_lo > 1) xcd_barrier(bar);
; __device__ __forceinline__ void xcd_barrier(const XcdBarrier& b) {
;     asm volatile("s_waitcnt vmcnt(0)" ::: "memory");
;     __syncthreads();
;     if (threadIdx.x == 0) {
; __global__ void __launch_bounds__(512, 2) mega(Params p) {
;     ...
;         CASE(11) sample_reduce<0>((const float*)(ws + O_SLAB), 4, nullptr, nullptr, 1.f, (const float*)(ws + O_ST2), p.in[22], p.in[23], XB, (float*)(ws + O_ST3), nullptr, nullptr, XB); SEAM(11)
.LBB0_1512:
	s_or_b64 exec, exec, s[12:13]
	s_waitcnt vmcnt(0) lgkmcnt(0)
	s_barrier
	s_cmpk_gt_u32 s2, 0x7f
	s_cbranch_scc1 .Lq11_prod_done
	s_mov_b64 s[38:39], exec
	v_readlane_b32 s0, v252, 6
	v_readlane_b32 s1, v252, 7
	s_and_b64 s[0:1], s[38:39], s[0:1]
	s_mov_b64 exec, s[0:1]
	s_cbranch_execz .Lq11_prod_restore
	buffer_wbl2 sc1
	s_waitcnt vmcnt(0)
	s_add_u32 s98, s52, 0x2fb468c0
	s_addc_u32 s99, s53, 0
	v_mov_b32_e32 v0, 0
	v_mov_b32_e32 v1, 1
	global_atomic_add v0, v1, s[98:99]
	s_waitcnt vmcnt(0)

; #define CASE(k) if (PH_ON(k) && ph_lo <= (k) && (k) < ph_hi)
; #define SEAM(k) if (ph_lo <= (k) && (k) < ph_hi && ph_hi - ph_lo > 1) xcd_barrier(bar);
; __global__ void __launch_bounds__(512, 2) mega(Params p) {
;     ...
;         for (int rep12 = 0; rep12 <= REP12; ++rep12)
;         CASE(12) { pg8::Gemm g{XB, (const bf16_t*)(ws + O_WGU2), M, 2 * FF, D, D}; pg8::StaticOrder S; S.init(M, 2 * FF, G, bx);
;             pg8::EpiSwiGLU E{ACT, (const float*)(ws + O_ST3), (const float*)(ws + O_C1) + C_GU2, (const float*)(ws + O_C2) + C_GU2};
;             pg8::gemm_phase<pg8::EpiSwiGLU, pg8::StaticOrder, true, true>(lds, g, S, E); if (rep12 < REP12) grid.sync(); } SEAM(12)
.LBB0_1558:
	s_cmp_lt_i32 s54, 13
	s_cselect_b64 s[0:1], -1, 0
	s_cmp_gt_i32 s55, 12
	s_cselect_b64 s[4:5], -1, 0
	s_and_b64 s[0:1], s[0:1], s[4:5]
	s_add_u32 s46, s52, 0x2f3e1000
	s_addc_u32 s47, s53, 0
	s_lshr_b32 s4, s3, 29
	s_add_i32 s4, s2, s4
	s_ashr_i32 s5, s4, 3
	s_and_b32 s4, s4, -8
	s_sub_i32 s33, s2, s4
	s_cmp_lt_i32 s33, 0
	s_cselect_b64 s[8:9], -1, 0
	s_cmp_gt_i32 s33, -1
	s_movk_i32 s4, 0x100
	s_cselect_b64 s[48:49], -1, 0
	v_cmp_gt_u32_e64 s[6:7], s4, v208
	s_add_i32 s4, 0, 0x20000
	s_andn2_b64 vcc, exec, s[0:1]
	v_lshl_add_u32 v192, v208, 3, s4
	s_cbranch_vccnz .LBB0_1623
	s_and_b32 s98, s2, 7
	s_cmp_lg_u32 s98, 7
	s_cbranch_scc1 .Lq11_skip
	s_add_u32 s98, s52, 0x2fb468c0
	s_addc_u32 s99, s53, 0
	s_mov_b32 s101, 0
	v_mov_b32_e32 v0, 0

; #define PG8_STAGE(bufoff, gbase, voff) do { _Pragma("unroll") for (int _i = 0; _i < 2; ++_i) \
;         __builtin_amdgcn_global_load_lds((const unsigned*)((const char*)(gbase) + (voff)[_i]), (LAS unsigned*)(lds + (bufoff) + ldsw + _i * 8192), 16, 0, 0); } while (0)
; #define PG8_WAIT_V(n) asm volatile("s_waitcnt vmcnt(" #n ")" ::: "memory")
; #define PG8_BAR __builtin_amdgcn_s_barrier()
; template <class Epi, class Sched, bool ALIGN_EPI = false, bool SP2 = false>
; __device__ __forceinline__ void gemm_phase(LAS unsigned char* lds, const Gemm g, const Sched& S, const Epi& E) {
;     ...
;     const int wid = __builtin_amdgcn_readfirstlane(tid >> 6), lane = tid & 63, wr = wid >> 2, wc = wid & 3, fr = lane & 15, fq = lane >> 4;
;     const int K = g.ldk, nt = g.K / BK;
;     unsigned voffA[2], voffB[2];
; #pragma unroll
;     for (int i = 0; i < 2; ++i) { int R, C; stage_rc(tid * 16 + i * 8192, R, C); const int Rb = Epi::PERM ? ((R & ~31) + perm32(R & 31)) : R;
;         voffA[i] = (unsigned)(R * K + C) * 2u; voffB[i] = (unsigned)(Rb * K + C) * 2u; }
;     const size_t kstep = (size_t)(BK * 2);
;     const size_t hstep = (size_t)HALF * K * 2;
;     const size_t tstep = 2 * hstep;
;     const unsigned ldsw = (unsigned)wid * 1024u;
;     const int aoff = lds_byte(wr * 64 + fr, fq * 8), boff = lds_byte(wc * 32 + fr, fq * 8);
;     ...
;     Unit cur, nxt; int ui = 0;
;     if (!S.next(0, cur)) return;
;     f32x4 acc[2][2][4][2];
; #pragma unroll
;     for (int a = 0; a < 2; ++a)
; #pragma unroll
;         for (int b = 0; b < 2; ++b)
; #pragma unroll
;             for (int m = 0; m < 4; ++m)
; #pragma unroll
;                 for (int n = 0; n < 2; ++n) acc[a][b][m][n] = (f32x4){0.f, 0.f, 0.f, 0.f};
;     bf16x8 At[4][2], B0[2][2], B1[2][2];
;     const char* cA = (const char*)g.A + (size_t)cur.pm * tstep + (size_t)cur.kofs * 2; const char* cB = (const char*)g.Bt + (size_t)cur.pn * tstep + (size_t)cur.kofs * 2;
;     if constexpr (SP2) {
;         PG8_STAGE(PG8_SB(0, 0), cB, voffB); PG8_STAGE(PG8_SB(0, 1), cB + hstep, voffB); PG8_STAGE(PG8_SA(0, 0), cA, voffA); PG8_STAGE(PG8_SA(0, 1), cA + hstep, voffA);
;         if (wr == 1) PG8_BAR;
;         PG8_WAIT_V(2); PG8_BAR;
;         PG8_STAGE(PG8_SB(1, 0), cB + kstep, voffB); PG8_STAGE(PG8_SA(1, 0), cA + kstep, voffA); PG8_STAGE(PG8_SB(1, 1), cB + hstep + kstep, voffB);
.Lq11_skip:
	s_waitcnt vmcnt(0)
	v_mov_b32_e32 v9, v208
	s_cmpk_gt_i32 s2, 0xb57
	s_nop 0
	v_readfirstlane_b32 s20, v9
	s_cbranch_scc1 .LBB0_1577
	s_waitcnt lgkmcnt(0)
	v_lshlrev_b32_e32 v0, 4, v9
	v_add_u32_e32 v1, 0x2000, v0
	v_ashrrev_i32_e32 v2, 31, v1
	v_lshrrev_b32_e32 v2, 22, v2
	v_add_u32_e32 v2, v1, v2
	v_ashrrev_i32_e32 v8, 10, v2
	v_mul_i32_i24_e32 v2, 0x400, v8
	v_sub_u32_e32 v1, v1, v2
	v_lshrrev_b32_e32 v2, 4, v1
	v_bitop3_b32 v1, v2, v1, 32 bitop3:0x6c
	v_ashrrev_i32_e32 v2, 31, v1
	v_lshrrev_b32_e32 v2, 26, v2
	v_add_u32_e32 v2, v1, v2
	v_lshlrev_b32_e32 v3, 3, v8
	v_ashrrev_i32_e32 v10, 6, v2
	v_and_b32_e32 v3, -16, v3
	v_add_u32_e32 v3, v10, v3
	v_and_b32_e32 v4, 3, v10
	s_mov_b32 s10, 0x1fffe0
	v_lshrrev_b32_e32 v5, 2, v3
	v_lshlrev_b32_e32 v6, 1, v3
	v_and_b32_e32 v2, 0xc0, v2
	v_and_or_b32 v4, v3, s10, v4
	v_and_b32_e32 v5, 4, v5
	v_and_b32_e32 v6, 24, v6
	v_sub_u32_e32 v1, v1, v2
	v_mov_b32_e32 v2, 1
	v_or3_b32 v4, v4, v5, v6
	v_lshlrev_b32_e32 v5, 5, v8
	v_ashrrev_i16_sdwa v1, v2, sext(v1) dst_sel:DWORD dst_unused:UNUSED_PAD src0_sel:DWORD src1_sel:BYTE_0
	v_and_b32_e32 v5, 32, v5
	v_bfe_i32 v11, v1, 0, 16
	v_add_lshl_u32 v1, v5, v11, 1
	v_lshl_add_u32 v128, v4, 11, v1
	v_lshl_add_u32 v130, v3, 11, v1
	v_bfe_i32 v1, v9, 27, 1
	v_lshrrev_b32_e32 v1, 22, v1
	v_add_u32_e32 v1, v0, v1
	s_ashr_i32 s14, s20, 6
	v_and_b32_e32 v1, 0xfffffc00, v1
	s_ashr_i32 s22, s20, 8
	s_lshl_b32 s0, s14, 10
	v_sub_u32_e32 v0, v0, v1
	s_add_u32 s1, s52, 0x1f81000
	v_lshrrev_b32_e32 v1, 4, v0
	v_ashrrev_i32_e32 v3, 31, v9
	s_addc_u32 s23, s53, 0
	v_bitop3_b32 v0, v1, v0, 32 bitop3:0x6c
	v_lshrrev_b32_e32 v3, 26, v3
	v_ashrrev_i32_e32 v1, 31, v0
	v_add_u32_e32 v3, v9, v3
	s_movk_i32 s40, 0x16c
	s_and_b64 s[8:9], s[8:9], exec
	v_lshrrev_b32_e32 v1, 26, v1
	v_ashrrev_i32_e32 v13, 6, v3
	s_cselect_b32 s8, s40, 0x16b
	v_add_u32_e32 v1, v0, v1
	v_lshlrev_b32_e32 v3, 3, v13
	s_mul_i32 s8, s33, s8
	v_ashrrev_i32_e32 v12, 6, v1
	v_and_b32_e32 v3, -16, v3
	s_add_i32 s8, s8, s5
	v_add_u32_e32 v3, v12, v3
	v_and_b32_e32 v4, 3, v12
	s_mul_hi_i32 s9, s8, 0x2e8ba2e9
	v_and_or_b32 v4, v3, s10, v4
	s_lshr_b32 s10, s9, 31
	s_ashr_i32 s9, s9, 5
	v_lshrrev_b32_e32 v5, 2, v3
	v_lshlrev_b32_e32 v6, 1, v3
	v_and_b32_e32 v1, 0xc0, v1
	s_add_i32 s9, s9, s10
	v_and_b32_e32 v5, 4, v5
	v_and_b32_e32 v6, 24, v6
	v_sub_u32_e32 v0, v0, v1
	s_lshl_b32 s10, s9, 3
	v_or3_b32 v4, v4, v5, v6
	v_lshlrev_b32_e32 v5, 5, v13
	v_ashrrev_i16_sdwa v0, v2, sext(v0) dst_sel:DWORD dst_unused:UNUSED_PAD src0_sel:DWORD src1_sel:BYTE_0
	s_sub_i32 s11, 0x84, s10
	v_and_b32_e32 v5, 32, v5
	v_bfe_i32 v14, v0, 0, 16
	s_min_u32 s11, s11, 8
	s_mulk_i32 s9, 0xb0
	v_add_lshl_u32 v0, v5, v14, 1
	s_sub_i32 s12, s8, s9
	v_cvt_f32_ubyte0_e32 v2, s11
	v_lshl_add_u32 v132, v4, 11, v0
	v_cvt_f32_i32_e32 v1, s12
	v_rcp_iflag_f32_e32 v4, v2
	v_lshl_add_u32 v134, v3, 11, v0
	s_ashr_i32 s8, s12, 30
	s_or_b32 s13, s8, 1
	v_mul_f32_e32 v0, v1, v4
	v_trunc_f32_e32 v0, v0
	v_fma_f32 v1, -v0, v2, v1
	v_cvt_i32_f32_e32 v0, v0
	v_cmp_ge_f32_e64 s[8:9], |v1|, v2
	s_and_b64 s[8:9], s[8:9], exec
	s_cselect_b32 s8, s13, 0
	v_readfirstlane_b32 s9, v0
	s_add_i32 s8, s9, s8
	s_mul_i32 s9, s8, s11
	s_sub_i32 s9, s12, s9
	s_sext_i32_i16 s9, s9
	s_add_i32 s10, s10, s9
	s_ashr_i32 s11, s10, 31
	s_bfe_i64 s[16:17], s[8:9], 0x100000
	s_lshl_b64 s[12:13], s[10:11], 19
	s_lshl_b64 s[16:17], s[16:17], 19
	s_add_u32 s34, s1, s16
	s_addc_u32 s35, s23, s17
	s_add_i32 s41, s0, 0
	s_add_i32 m0, s41, 0x10000
	v_mov_b32_e32 v133, 0
	global_load_lds_dwordx4 v132, s[34:35]
	s_add_i32 m0, s41, 0x12000
	s_add_u32 s16, s34, 0x40000
	global_load_lds_dwordx4 v128, s[34:35]
	s_addc_u32 s17, s35, 0
	s_add_i32 m0, s41, 0x14000
	v_mov_b32_e32 v129, v133
	global_load_lds_dwordx4 v132, s[16:17]
	s_add_i32 m0, s41, 0x16000
	s_add_u32 s36, s42, s12
	s_addc_u32 s37, s43, s13
	s_add_i32 s50, s41, 0x2000
	global_load_lds_dwordx4 v128, s[16:17]
	s_mov_b32 m0, s41
	s_add_u32 s12, s36, 0x40000
	global_load_lds_dwordx4 v134, s[36:37]
	s_mov_b32 m0, s50
	s_addc_u32 s13, s37, 0
	s_add_i32 s51, s41, 0x4000
	global_load_lds_dwordx4 v130, s[36:37]
	s_mov_b32 m0, s51
	s_add_i32 s56, s41, 0x6000
	global_load_lds_dwordx4 v134, s[12:13]
	s_mov_b32 m0, s56
	v_mov_b32_e32 v135, v133
	global_load_lds_dwordx4 v130, s[12:13]
	v_mov_b32_e32 v131, v133
	s_cmp_eq_u32 s22, 1
	s_mov_b32 s57, 0
	v_lshl_add_u64 v[6:7], s[34:35], 0, v[132:133]
	v_lshl_add_u64 v[4:5], s[34:35], 0, v[128:129]
	v_lshl_add_u64 v[0:1], s[36:37], 0, v[134:135]
	s_cselect_b64 s[12:13], -1, 0
	s_cmp_lg_u32 s22, 1
	v_lshl_add_u64 v[2:3], s[36:37], 0, v[130:131]
	s_cbranch_scc1 .LBB0_1562
	s_barrier
